# ph3->ph4 and ph4->ph1 seams: barrier among the 32 workgroups of one blockIdx%8 group (agent-scope release before arrival, agent-scope acquire issued right after arrival and overlapped with the poll)
# baseline (speedup 1.0000x reference)
.LBB0_665:
	s_add_i32 s28, s8, 4
	s_cmp_lt_i32 s28, s45
	s_cselect_b64 s[20:21], -1, 0
	s_and_b64 s[12:13], s[12:13], s[20:21]
	s_andn2_b64 vcc, exec, s[12:13]
	s_cbranch_vccnz .LBB0_719
	s_cmp_lg_u32 s3, 0x100
	s_cbranch_scc1 .Lgb_orig_a
	s_waitcnt vmcnt(0) lgkmcnt(0)
	s_barrier
	v_readlane_b32 s98, v251, 20
	v_readlane_b32 s99, v251, 21
	s_nop 3
	s_mov_b64 exec, s[98:99]
	s_cbranch_execz .Lgb_done_a
	buffer_wbl2 sc1
	s_waitcnt vmcnt(0)
	v_readlane_b32 s98, v251, 2
	s_nop 3
	s_and_b32 s98, s98, 7
	s_lshl_b32 s98, s98, 8
	s_add_u32 s98, s98, 0x3800
	v_mov_b32_e32 v0, s98
	v_mov_b32_e32 v1, 1
	v_mov_b32_e32 v3, 0
	v_readlane_b32 s100, v254, 13
	s_nop 3
	s_lshl_b32 s100, s100, 1
	s_add_i32 s100, s100, 1
	s_lshl_b32 s100, s100, 5
	v_readlane_b32 s98, v251, 18
	v_readlane_b32 s99, v251, 19
	s_nop 7
	global_atomic_add v0, v1, s[98:99]
	buffer_inv sc1

.Lgb_rel_a:
.Lgb_done_a:
	s_mov_b64 exec, -1
	s_barrier
	s_branch .LBB0_719

.LBB0_758:
	s_add_i32 s10, s8, 5
	s_cmp_ge_i32 s10, s45
	s_cbranch_scc1 .LBB0_206
	s_cmp_lg_u32 s3, 0x100
	s_cbranch_scc1 .Lgb_orig_b
	v_readlane_b32 s98, v254, 13
	s_nop 3
	s_cmp_ge_u32 s98, 3
	s_cbranch_scc1 .Lgb_orig_b
	s_waitcnt vmcnt(0) lgkmcnt(0)
	s_barrier
	v_readlane_b32 s98, v251, 20
	v_readlane_b32 s99, v251, 21
	s_nop 3
	s_mov_b64 exec, s[98:99]
	s_cbranch_execz .Lgb_done_b
	buffer_wbl2 sc1
	s_waitcnt vmcnt(0)
	v_readlane_b32 s98, v251, 2
	s_nop 3
	s_and_b32 s98, s98, 7
	s_lshl_b32 s98, s98, 8
	s_add_u32 s98, s98, 0x3800
	v_mov_b32_e32 v0, s98
	v_mov_b32_e32 v1, 1
	v_mov_b32_e32 v3, 0
	v_readlane_b32 s100, v254, 13
	s_nop 3
	s_lshl_b32 s100, s100, 1
	s_add_i32 s100, s100, 2
	s_lshl_b32 s100, s100, 5
	v_readlane_b32 s98, v251, 18
	v_readlane_b32 s99, v251, 19
	s_nop 7
	global_atomic_add v0, v1, s[98:99]
	buffer_inv sc1
